# group-barrier poll sleep 2->1 and nt on the prologue's PB (bf16 p) stores
# speedup vs baseline: 1.0034x; 1.0034x over previous
; __device__ __forceinline__ void group_barrier(unsigned* ctr, unsigned& gen, const bool same_xcc) {
;     ...
;     if (tid_l == 0) {
;         if (!same_xcc) {
;             __builtin_amdgcn_fence(__ATOMIC_RELEASE, "agent");
;             asm volatile("s_waitcnt vmcnt(0)" ::: "memory"); }
;         __hip_atomic_fetch_add(ctr, 1u, __ATOMIC_RELAXED, __HIP_MEMORY_SCOPE_AGENT);
;         while (__hip_atomic_load(ctr, __ATOMIC_RELAXED, __HIP_MEMORY_SCOPE_AGENT) < gen) __builtin_amdgcn_s_sleep(2);
;         __builtin_amdgcn_fence(__ATOMIC_ACQUIRE, "agent");
;         asm volatile("s_waitcnt vmcnt(0)" ::: "memory");
;     }
.LBB0_236:
	s_sleep 1
	global_load_dword v0, v193, s[4:5] sc1
	s_waitcnt vmcnt(0)
	v_cmp_gt_u32_e32 vcc, s2, v0
	s_cbranch_vccnz .LBB0_236

; __device__ __forceinline__ void group_barrier(unsigned* ctr, unsigned& gen, const bool same_xcc) {
;     ...
;     if (tid_l == 0) {
;         if (!same_xcc) {
;             __builtin_amdgcn_fence(__ATOMIC_RELEASE, "agent");
;             asm volatile("s_waitcnt vmcnt(0)" ::: "memory"); }
;         __hip_atomic_fetch_add(ctr, 1u, __ATOMIC_RELAXED, __HIP_MEMORY_SCOPE_AGENT);
;         while (__hip_atomic_load(ctr, __ATOMIC_RELAXED, __HIP_MEMORY_SCOPE_AGENT) < gen) __builtin_amdgcn_s_sleep(2);
;         __builtin_amdgcn_fence(__ATOMIC_ACQUIRE, "agent");
;         asm volatile("s_waitcnt vmcnt(0)" ::: "memory");
;     }
.LBB0_393:
	s_sleep 1
	global_load_dword v0, v193, s[6:7] sc1
	s_waitcnt vmcnt(0)
	v_cmp_gt_u32_e32 vcc, s2, v0
	s_cbranch_vccnz .LBB0_393

; __device__ __forceinline__ void group_barrier(unsigned* ctr, unsigned& gen, const bool same_xcc) {
;     ...
;     if (tid_l == 0) {
;         if (!same_xcc) {
;             __builtin_amdgcn_fence(__ATOMIC_RELEASE, "agent");
;             asm volatile("s_waitcnt vmcnt(0)" ::: "memory"); }
;         __hip_atomic_fetch_add(ctr, 1u, __ATOMIC_RELAXED, __HIP_MEMORY_SCOPE_AGENT);
;         while (__hip_atomic_load(ctr, __ATOMIC_RELAXED, __HIP_MEMORY_SCOPE_AGENT) < gen) __builtin_amdgcn_s_sleep(2);
;         __builtin_amdgcn_fence(__ATOMIC_ACQUIRE, "agent");
;         asm volatile("s_waitcnt vmcnt(0)" ::: "memory");
;     }
.LBB0_610:
	s_sleep 1
	global_load_dword v0, v193, s[4:5] sc1
	s_waitcnt vmcnt(0)
	v_cmp_gt_u32_e32 vcc, s2, v0
	s_cbranch_vccnz .LBB0_610
	s_branch .LBB0_224
